# LDS-DMA attention loop with the last K/V tile peeled: no prefetch of a non-existent 35th tile, no buffer flips or DMA wait on the last tile
# speedup vs baseline: 1.0270x; 1.0001x over previous
.Lattn_nf_loop:
	ds_read_b128 v[98:101], v82 offset:0
	ds_read_b128 v[102:105], v83 offset:0
	ds_read_b128 v[106:109], v84 offset:0
	ds_read_b128 v[110:113], v85 offset:0
	s_and_b32 s10, s15, 1
	s_xor_b32 s10, s10, 1
	s_lshl_b32 s10, s10, 15
	s_add_i32 s10, s10, s11
	s_add_i32 s6, s10, 0x10000
	s_waitcnt lgkmcnt(3)
	v_mfma_f32_32x32x16_bf16 v[138:153], v[98:101], v[10:13], 0
	ds_read_b128 v[98:101], v82 offset:8192
	s_add_i32 m0, s10, 0x0
	s_nop 0
	global_load_lds_dwordx4 v124, s[64:65]
	s_waitcnt lgkmcnt(3)
	v_mfma_f32_32x32x16_bf16 v[138:153], v[102:105], v[14:17], v[138:153]
	ds_read_b128 v[102:105], v83 offset:8192
	s_add_i32 m0, s10, 0x2000
	s_nop 0
	global_load_lds_dwordx4 v124, s[66:67]
	s_waitcnt lgkmcnt(3)
	v_mfma_f32_32x32x16_bf16 v[138:153], v[106:109], v[2:5], v[138:153]
	ds_read_b128 v[106:109], v84 offset:8192
	s_add_i32 m0, s10, 0x4000
	s_nop 0
	global_load_lds_dwordx4 v124, s[68:69]
	s_waitcnt lgkmcnt(3)
	v_mfma_f32_32x32x16_bf16 v[138:153], v[110:113], v[6:9], v[138:153]
	ds_read_b128 v[110:113], v85 offset:8192
	s_add_i32 m0, s10, 0x6000
	s_nop 0
	global_load_lds_dwordx4 v124, s[70:71]
	v_add_u32_e32 v124, s36, v124
	s_waitcnt lgkmcnt(3)
	v_mfma_f32_32x32x16_bf16 v[154:169], v[98:101], v[10:13], 0
	ds_read_b128 v[98:101], v82 offset:16384
	s_add_i32 m0, s6, 0x0
	s_nop 0
	global_load_lds_dwordx4 v125, s[72:73]
	ds_read_b128 v[128:131], v86 offset:0
	ds_read_b128 v[184:187], v86 offset:8192
	v_exp_f32_e32 v138, v138
	v_exp_f32_e32 v139, v139
	v_exp_f32_e32 v140, v140
	v_exp_f32_e32 v141, v141
	v_exp_f32_e32 v142, v142
	v_exp_f32_e32 v143, v143
	s_waitcnt lgkmcnt(5)
	v_mfma_f32_32x32x16_bf16 v[154:169], v[102:105], v[14:17], v[154:169]
	ds_read_b128 v[102:105], v83 offset:16384
	s_add_i32 m0, s6, 0x2000
	s_nop 0
	global_load_lds_dwordx4 v125, s[74:75]
	ds_read_b128 v[188:191], v86 offset:16384
	ds_read_b128 v[192:195], v86 offset:24576
	v_exp_f32_e32 v144, v144
	v_exp_f32_e32 v145, v145
	v_add_f32_e32 v122, v138, v122
	v_add_f32_e32 v122, v139, v122
	v_add_f32_e32 v122, v140, v122
	v_add_f32_e32 v122, v141, v122
	v_add_f32_e32 v122, v142, v122
	v_add_f32_e32 v122, v143, v122
	v_add_f32_e32 v122, v144, v122
	v_add_f32_e32 v122, v145, v122
	v_cvt_pk_bf16_f32 v114, v138, v139
	v_cvt_pk_bf16_f32 v115, v140, v141
	v_cvt_pk_bf16_f32 v116, v142, v143
	v_cvt_pk_bf16_f32 v117, v144, v145
	s_waitcnt lgkmcnt(7)
	v_mfma_f32_32x32x16_bf16 v[154:169], v[106:109], v[2:5], v[154:169]
	ds_read_b128 v[106:109], v84 offset:16384
	s_add_i32 m0, s6, 0x4000
	s_nop 0
	global_load_lds_dwordx4 v125, s[76:77]
	ds_read_b128 v[196:199], v87 offset:0
	v_exp_f32_e32 v146, v146
	v_exp_f32_e32 v147, v147
	s_waitcnt lgkmcnt(8)
	v_mfma_f32_32x32x16_bf16 v[154:169], v[110:113], v[6:9], v[154:169]
	ds_read_b128 v[110:113], v85 offset:16384
	s_add_i32 m0, s6, 0x6000
	s_nop 0
	global_load_lds_dwordx4 v125, s[78:79]
	v_add_u32_e32 v125, s38, v125
	ds_read_b128 v[216:219], v87 offset:8192
	v_exp_f32_e32 v148, v148
	v_exp_f32_e32 v149, v149
	s_waitcnt lgkmcnt(8)
	v_mfma_f32_32x32x16_bf16 v[18:33], v[128:131], v[114:117], v[18:33]
	v_exp_f32_e32 v150, v150
	v_exp_f32_e32 v151, v151
	s_waitcnt lgkmcnt(7)
	v_mfma_f32_32x32x16_bf16 v[34:49], v[184:187], v[114:117], v[34:49]
	ds_read_b128 v[200:203], v87 offset:16384
	v_exp_f32_e32 v152, v152
	v_exp_f32_e32 v153, v153
	s_waitcnt lgkmcnt(6)
	v_mfma_f32_32x32x16_bf16 v[50:65], v[188:191], v[114:117], v[50:65]
	ds_read_b128 v[204:207], v87 offset:24576
	v_add_f32_e32 v122, v146, v122
	v_add_f32_e32 v122, v147, v122
	v_add_f32_e32 v122, v148, v122
	v_add_f32_e32 v122, v149, v122
	s_waitcnt lgkmcnt(6)
	v_mfma_f32_32x32x16_bf16 v[66:81], v[192:195], v[114:117], v[66:81]
	v_add_f32_e32 v122, v150, v122
	v_add_f32_e32 v122, v151, v122
	v_add_f32_e32 v122, v152, v122
	v_add_f32_e32 v122, v153, v122
	v_cvt_pk_bf16_f32 v118, v146, v147
	v_cvt_pk_bf16_f32 v119, v148, v149
	v_cvt_pk_bf16_f32 v120, v150, v151
	v_cvt_pk_bf16_f32 v121, v152, v153
	v_mfma_f32_32x32x16_bf16 v[138:153], v[98:101], v[10:13], 0
	ds_read_b128 v[98:101], v82 offset:24576
	ds_read_b128 v[128:131], v88 offset:0
	v_exp_f32_e32 v154, v154
	v_exp_f32_e32 v155, v155
	v_mfma_f32_32x32x16_bf16 v[138:153], v[102:105], v[14:17], v[138:153]
	ds_read_b128 v[102:105], v83 offset:24576
	ds_read_b128 v[184:187], v88 offset:8192
	v_exp_f32_e32 v156, v156
	v_exp_f32_e32 v157, v157
	s_waitcnt lgkmcnt(8)
	v_mfma_f32_32x32x16_bf16 v[18:33], v[196:199], v[118:121], v[18:33]
	v_exp_f32_e32 v158, v158
	v_exp_f32_e32 v159, v159
	s_waitcnt lgkmcnt(6)
	v_mfma_f32_32x32x16_bf16 v[34:49], v[216:219], v[118:121], v[34:49]
	ds_read_b128 v[188:191], v88 offset:16384
	v_exp_f32_e32 v160, v160
	v_exp_f32_e32 v161, v161
	s_waitcnt lgkmcnt(6)
	v_mfma_f32_32x32x16_bf16 v[50:65], v[200:203], v[118:121], v[50:65]
	ds_read_b128 v[192:195], v88 offset:24576
	v_add_f32_e32 v122, v154, v122
	v_add_f32_e32 v122, v155, v122
	v_add_f32_e32 v122, v156, v122
	v_add_f32_e32 v122, v157, v122
	s_waitcnt lgkmcnt(6)
	v_mfma_f32_32x32x16_bf16 v[66:81], v[204:207], v[118:121], v[66:81]
	v_add_f32_e32 v122, v158, v122
	v_add_f32_e32 v122, v159, v122
	v_add_f32_e32 v122, v160, v122
	v_add_f32_e32 v122, v161, v122
	v_cvt_pk_bf16_f32 v114, v154, v155
	v_cvt_pk_bf16_f32 v115, v156, v157
	v_cvt_pk_bf16_f32 v116, v158, v159
	v_cvt_pk_bf16_f32 v117, v160, v161
	v_mfma_f32_32x32x16_bf16 v[138:153], v[106:109], v[2:5], v[138:153]
	ds_read_b128 v[106:109], v84 offset:24576
	ds_read_b128 v[196:199], v89 offset:0
	v_exp_f32_e32 v162, v162
	v_exp_f32_e32 v163, v163
	v_mfma_f32_32x32x16_bf16 v[138:153], v[110:113], v[6:9], v[138:153]
	ds_read_b128 v[110:113], v85 offset:24576
	ds_read_b128 v[216:219], v89 offset:8192
	v_exp_f32_e32 v164, v164
	v_exp_f32_e32 v165, v165
	s_waitcnt lgkmcnt(8)
	v_mfma_f32_32x32x16_bf16 v[18:33], v[128:131], v[114:117], v[18:33]
	v_exp_f32_e32 v166, v166
	v_exp_f32_e32 v167, v167
	s_waitcnt lgkmcnt(6)
	v_mfma_f32_32x32x16_bf16 v[34:49], v[184:187], v[114:117], v[34:49]
	ds_read_b128 v[200:203], v89 offset:16384
	v_exp_f32_e32 v168, v168
	v_exp_f32_e32 v169, v169
	s_waitcnt lgkmcnt(6)
	v_mfma_f32_32x32x16_bf16 v[50:65], v[188:191], v[114:117], v[50:65]
	ds_read_b128 v[204:207], v89 offset:24576
	v_add_f32_e32 v122, v162, v122
	v_add_f32_e32 v122, v163, v122
	v_add_f32_e32 v122, v164, v122
	v_add_f32_e32 v122, v165, v122
	s_waitcnt lgkmcnt(6)
	v_mfma_f32_32x32x16_bf16 v[66:81], v[192:195], v[114:117], v[66:81]
	v_add_f32_e32 v122, v166, v122
	v_add_f32_e32 v122, v167, v122
	v_add_f32_e32 v122, v168, v122
	v_add_f32_e32 v122, v169, v122
	v_cvt_pk_bf16_f32 v118, v162, v163
	v_cvt_pk_bf16_f32 v119, v164, v165
	v_cvt_pk_bf16_f32 v120, v166, v167
	v_cvt_pk_bf16_f32 v121, v168, v169
	v_mfma_f32_32x32x16_bf16 v[154:169], v[98:101], v[10:13], 0
	ds_read_b128 v[128:131], v90 offset:0
	v_exp_f32_e32 v138, v138
	v_exp_f32_e32 v139, v139
	v_mfma_f32_32x32x16_bf16 v[154:169], v[102:105], v[14:17], v[154:169]
	ds_read_b128 v[184:187], v90 offset:8192
	v_exp_f32_e32 v140, v140
	v_exp_f32_e32 v141, v141
	s_waitcnt lgkmcnt(6)
	v_mfma_f32_32x32x16_bf16 v[18:33], v[196:199], v[118:121], v[18:33]
	v_exp_f32_e32 v142, v142
	v_exp_f32_e32 v143, v143
	s_waitcnt lgkmcnt(4)
	v_mfma_f32_32x32x16_bf16 v[34:49], v[216:219], v[118:121], v[34:49]
	ds_read_b128 v[188:191], v90 offset:16384
	v_exp_f32_e32 v144, v144
	v_exp_f32_e32 v145, v145
	s_waitcnt lgkmcnt(4)
	v_mfma_f32_32x32x16_bf16 v[50:65], v[200:203], v[118:121], v[50:65]
	ds_read_b128 v[192:195], v90 offset:24576
	v_add_f32_e32 v122, v138, v122
	v_add_f32_e32 v122, v139, v122
	v_add_f32_e32 v122, v140, v122
	v_add_f32_e32 v122, v141, v122
	s_waitcnt lgkmcnt(4)
	v_mfma_f32_32x32x16_bf16 v[66:81], v[204:207], v[118:121], v[66:81]
	v_add_f32_e32 v122, v142, v122
	v_add_f32_e32 v122, v143, v122
	v_add_f32_e32 v122, v144, v122
	v_add_f32_e32 v122, v145, v122
	v_cvt_pk_bf16_f32 v114, v138, v139
	v_cvt_pk_bf16_f32 v115, v140, v141
	v_cvt_pk_bf16_f32 v116, v142, v143
	v_cvt_pk_bf16_f32 v117, v144, v145
	v_mfma_f32_32x32x16_bf16 v[154:169], v[106:109], v[2:5], v[154:169]
	ds_read_b128 v[196:199], v91 offset:0
	v_exp_f32_e32 v146, v146
	v_exp_f32_e32 v147, v147
	v_mfma_f32_32x32x16_bf16 v[154:169], v[110:113], v[6:9], v[154:169]
	ds_read_b128 v[216:219], v91 offset:8192
	v_exp_f32_e32 v148, v148
	v_exp_f32_e32 v149, v149
	s_waitcnt lgkmcnt(5)
	v_mfma_f32_32x32x16_bf16 v[18:33], v[128:131], v[114:117], v[18:33]
	v_exp_f32_e32 v150, v150
	v_exp_f32_e32 v151, v151
	s_waitcnt lgkmcnt(4)
	v_mfma_f32_32x32x16_bf16 v[34:49], v[184:187], v[114:117], v[34:49]
	ds_read_b128 v[200:203], v91 offset:16384
	v_exp_f32_e32 v152, v152
	v_exp_f32_e32 v153, v153
	s_waitcnt lgkmcnt(4)
	v_mfma_f32_32x32x16_bf16 v[50:65], v[188:191], v[114:117], v[50:65]
	ds_read_b128 v[204:207], v91 offset:24576
	v_add_f32_e32 v122, v146, v122
	v_add_f32_e32 v122, v147, v122
	v_add_f32_e32 v122, v148, v122
	v_add_f32_e32 v122, v149, v122
	s_waitcnt lgkmcnt(4)
	v_mfma_f32_32x32x16_bf16 v[66:81], v[192:195], v[114:117], v[66:81]
	v_add_f32_e32 v122, v150, v122
	v_add_f32_e32 v122, v151, v122
	v_add_f32_e32 v122, v152, v122
	v_add_f32_e32 v122, v153, v122
	v_cvt_pk_bf16_f32 v118, v146, v147
	v_cvt_pk_bf16_f32 v119, v148, v149
	v_cvt_pk_bf16_f32 v120, v150, v151
	v_cvt_pk_bf16_f32 v121, v152, v153
	s_waitcnt lgkmcnt(3)
	s_nop 0
	v_mfma_f32_32x32x16_bf16 v[18:33], v[196:199], v[118:121], v[18:33]
	ds_read_b128 v[128:131], v92 offset:0
	v_exp_f32_e32 v154, v154
	v_exp_f32_e32 v155, v155
	v_exp_f32_e32 v156, v156
	s_waitcnt lgkmcnt(3)
	v_mfma_f32_32x32x16_bf16 v[34:49], v[216:219], v[118:121], v[34:49]
	ds_read_b128 v[184:187], v92 offset:8192
	v_exp_f32_e32 v157, v157
	v_exp_f32_e32 v158, v158
	v_exp_f32_e32 v159, v159
	v_exp_f32_e32 v160, v160
	s_waitcnt lgkmcnt(3)
	v_mfma_f32_32x32x16_bf16 v[50:65], v[200:203], v[118:121], v[50:65]
	ds_read_b128 v[188:191], v92 offset:16384
	v_exp_f32_e32 v161, v161
	v_add_f32_e32 v122, v154, v122
	v_add_f32_e32 v122, v155, v122
	v_add_f32_e32 v122, v156, v122
	v_add_f32_e32 v122, v157, v122
	v_add_f32_e32 v122, v158, v122
	s_waitcnt lgkmcnt(3)
	v_mfma_f32_32x32x16_bf16 v[66:81], v[204:207], v[118:121], v[66:81]
	ds_read_b128 v[192:195], v92 offset:24576
	v_add_f32_e32 v122, v159, v122
	v_add_f32_e32 v122, v160, v122
	v_add_f32_e32 v122, v161, v122
	v_xor_b32_e32 v82, 0x8000, v82
	v_xor_b32_e32 v83, 0x8000, v83
	v_xor_b32_e32 v84, 0x8000, v84
	v_xor_b32_e32 v85, 0x8000, v85
	v_cvt_pk_bf16_f32 v114, v154, v155
	v_cvt_pk_bf16_f32 v115, v156, v157
	v_cvt_pk_bf16_f32 v116, v158, v159
	v_cvt_pk_bf16_f32 v117, v160, v161
	s_waitcnt lgkmcnt(3)
	s_nop 0
	v_mfma_f32_32x32x16_bf16 v[18:33], v[128:131], v[114:117], v[18:33]
	ds_read_b128 v[196:199], v93 offset:0
	v_exp_f32_e32 v162, v162
	v_exp_f32_e32 v163, v163
	v_exp_f32_e32 v164, v164
	s_waitcnt lgkmcnt(3)
	v_mfma_f32_32x32x16_bf16 v[34:49], v[184:187], v[114:117], v[34:49]
	ds_read_b128 v[216:219], v93 offset:8192
	v_exp_f32_e32 v165, v165
	v_exp_f32_e32 v166, v166
	v_exp_f32_e32 v167, v167
	s_waitcnt lgkmcnt(3)
	v_mfma_f32_32x32x16_bf16 v[50:65], v[188:191], v[114:117], v[50:65]
	ds_read_b128 v[200:203], v93 offset:16384
	v_exp_f32_e32 v168, v168
	v_exp_f32_e32 v169, v169
	v_add_f32_e32 v122, v162, v122
	v_add_f32_e32 v122, v163, v122
	s_waitcnt lgkmcnt(3)
	v_mfma_f32_32x32x16_bf16 v[66:81], v[192:195], v[114:117], v[66:81]
	ds_read_b128 v[204:207], v93 offset:24576
	v_add_f32_e32 v122, v164, v122
	v_add_f32_e32 v122, v165, v122
	v_add_f32_e32 v122, v166, v122
	v_add_f32_e32 v122, v167, v122
	v_add_f32_e32 v122, v168, v122
	v_add_f32_e32 v122, v169, v122
	v_cvt_pk_bf16_f32 v118, v162, v163
	v_cvt_pk_bf16_f32 v119, v164, v165
	v_cvt_pk_bf16_f32 v120, v166, v167
	v_cvt_pk_bf16_f32 v121, v168, v169
	s_waitcnt lgkmcnt(3)
	s_nop 0
	v_mfma_f32_32x32x16_bf16 v[18:33], v[196:199], v[118:121], v[18:33]
	v_xor_b32_e32 v86, 0x8000, v86
	v_xor_b32_e32 v87, 0x8000, v87
	s_waitcnt lgkmcnt(2)
	v_mfma_f32_32x32x16_bf16 v[34:49], v[216:219], v[118:121], v[34:49]
	v_xor_b32_e32 v88, 0x8000, v88
	v_xor_b32_e32 v89, 0x8000, v89
	s_waitcnt lgkmcnt(1)
	v_mfma_f32_32x32x16_bf16 v[50:65], v[200:203], v[118:121], v[50:65]
	v_xor_b32_e32 v90, 0x8000, v90
	v_xor_b32_e32 v91, 0x8000, v91
	s_waitcnt lgkmcnt(0)
	v_mfma_f32_32x32x16_bf16 v[66:81], v[204:207], v[118:121], v[66:81]
	v_xor_b32_e32 v92, 0x8000, v92
	v_xor_b32_e32 v93, 0x8000, v93
	s_waitcnt vmcnt(0)
	s_waitcnt lgkmcnt(0)
	s_barrier
	s_add_i32 s15, s15, 1
	s_cmp_eq_u32 s15, 33
	s_cbranch_scc0 .Lattn_nf_loop
	ds_read_b128 v[98:101], v82 offset:0
	ds_read_b128 v[102:105], v83 offset:0
	ds_read_b128 v[106:109], v84 offset:0
	ds_read_b128 v[110:113], v85 offset:0
	s_waitcnt lgkmcnt(3)
	v_mfma_f32_32x32x16_bf16 v[138:153], v[98:101], v[10:13], 0
	ds_read_b128 v[98:101], v82 offset:8192
	s_waitcnt lgkmcnt(3)
	v_mfma_f32_32x32x16_bf16 v[138:153], v[102:105], v[14:17], v[138:153]
	ds_read_b128 v[102:105], v83 offset:8192
	s_waitcnt lgkmcnt(3)
	v_mfma_f32_32x32x16_bf16 v[138:153], v[106:109], v[2:5], v[138:153]
	ds_read_b128 v[106:109], v84 offset:8192
	s_waitcnt lgkmcnt(3)
	v_mfma_f32_32x32x16_bf16 v[138:153], v[110:113], v[6:9], v[138:153]
	ds_read_b128 v[110:113], v85 offset:8192
	s_waitcnt lgkmcnt(3)
	v_mfma_f32_32x32x16_bf16 v[154:169], v[98:101], v[10:13], 0
	ds_read_b128 v[98:101], v82 offset:16384
	ds_read_b128 v[128:131], v86 offset:0
	ds_read_b128 v[184:187], v86 offset:8192
	s_nop 5
	v_exp_f32_e32 v138, v138
	v_exp_f32_e32 v139, v139
	v_exp_f32_e32 v140, v140
	v_exp_f32_e32 v141, v141
	v_exp_f32_e32 v142, v142
	v_exp_f32_e32 v143, v143
	s_waitcnt lgkmcnt(5)
	v_mfma_f32_32x32x16_bf16 v[154:169], v[102:105], v[14:17], v[154:169]
	ds_read_b128 v[102:105], v83 offset:16384
	ds_read_b128 v[188:191], v86 offset:16384
	ds_read_b128 v[192:195], v86 offset:24576
	v_exp_f32_e32 v144, v144
	v_exp_f32_e32 v145, v145
	v_add_f32_e32 v122, v138, v122
	v_add_f32_e32 v122, v139, v122
	v_add_f32_e32 v122, v140, v122
	v_add_f32_e32 v122, v141, v122
	v_add_f32_e32 v122, v142, v122
	v_add_f32_e32 v122, v143, v122
	v_add_f32_e32 v122, v144, v122
	v_add_f32_e32 v122, v145, v122
	v_cvt_pk_bf16_f32 v114, v138, v139
	v_cvt_pk_bf16_f32 v115, v140, v141
	v_cvt_pk_bf16_f32 v116, v142, v143
	v_cvt_pk_bf16_f32 v117, v144, v145
	s_waitcnt lgkmcnt(7)
	v_mfma_f32_32x32x16_bf16 v[154:169], v[106:109], v[2:5], v[154:169]
	ds_read_b128 v[106:109], v84 offset:16384
	ds_read_b128 v[196:199], v87 offset:0
	v_exp_f32_e32 v146, v146
	v_exp_f32_e32 v147, v147
	s_waitcnt lgkmcnt(8)
	v_mfma_f32_32x32x16_bf16 v[154:169], v[110:113], v[6:9], v[154:169]
	ds_read_b128 v[110:113], v85 offset:16384
	ds_read_b128 v[216:219], v87 offset:8192
	v_exp_f32_e32 v148, v148
	v_exp_f32_e32 v149, v149
	s_waitcnt lgkmcnt(8)
	v_mfma_f32_32x32x16_bf16 v[18:33], v[128:131], v[114:117], v[18:33]
	v_exp_f32_e32 v150, v150
	v_exp_f32_e32 v151, v151
	s_waitcnt lgkmcnt(7)
	v_mfma_f32_32x32x16_bf16 v[34:49], v[184:187], v[114:117], v[34:49]
	ds_read_b128 v[200:203], v87 offset:16384
	v_exp_f32_e32 v152, v152
	v_exp_f32_e32 v153, v153
	s_waitcnt lgkmcnt(6)
	v_mfma_f32_32x32x16_bf16 v[50:65], v[188:191], v[114:117], v[50:65]
	ds_read_b128 v[204:207], v87 offset:24576
	v_add_f32_e32 v122, v146, v122
	v_add_f32_e32 v122, v147, v122
	v_add_f32_e32 v122, v148, v122
	v_add_f32_e32 v122, v149, v122
	s_waitcnt lgkmcnt(6)
	v_mfma_f32_32x32x16_bf16 v[66:81], v[192:195], v[114:117], v[66:81]
	v_add_f32_e32 v122, v150, v122
	v_add_f32_e32 v122, v151, v122
	v_add_f32_e32 v122, v152, v122
	v_add_f32_e32 v122, v153, v122
	v_cvt_pk_bf16_f32 v118, v146, v147
	v_cvt_pk_bf16_f32 v119, v148, v149
	v_cvt_pk_bf16_f32 v120, v150, v151
	v_cvt_pk_bf16_f32 v121, v152, v153
	v_mfma_f32_32x32x16_bf16 v[138:153], v[98:101], v[10:13], 0
	ds_read_b128 v[98:101], v82 offset:24576
	ds_read_b128 v[128:131], v88 offset:0
	v_exp_f32_e32 v154, v154
	v_exp_f32_e32 v155, v155
	v_mfma_f32_32x32x16_bf16 v[138:153], v[102:105], v[14:17], v[138:153]
	ds_read_b128 v[102:105], v83 offset:24576
	ds_read_b128 v[184:187], v88 offset:8192
	v_exp_f32_e32 v156, v156
	v_exp_f32_e32 v157, v157
	s_waitcnt lgkmcnt(8)
	v_mfma_f32_32x32x16_bf16 v[18:33], v[196:199], v[118:121], v[18:33]
	v_exp_f32_e32 v158, v158
	v_exp_f32_e32 v159, v159
	s_waitcnt lgkmcnt(6)
	v_mfma_f32_32x32x16_bf16 v[34:49], v[216:219], v[118:121], v[34:49]
	ds_read_b128 v[188:191], v88 offset:16384
	v_exp_f32_e32 v160, v160
	v_exp_f32_e32 v161, v161
	s_waitcnt lgkmcnt(6)
	v_mfma_f32_32x32x16_bf16 v[50:65], v[200:203], v[118:121], v[50:65]
	ds_read_b128 v[192:195], v88 offset:24576
	v_add_f32_e32 v122, v154, v122
	v_add_f32_e32 v122, v155, v122
	v_add_f32_e32 v122, v156, v122
	v_add_f32_e32 v122, v157, v122
	s_waitcnt lgkmcnt(6)
	v_mfma_f32_32x32x16_bf16 v[66:81], v[204:207], v[118:121], v[66:81]
	v_add_f32_e32 v122, v158, v122
	v_add_f32_e32 v122, v159, v122
	v_add_f32_e32 v122, v160, v122
	v_add_f32_e32 v122, v161, v122
	v_cvt_pk_bf16_f32 v114, v154, v155
	v_cvt_pk_bf16_f32 v115, v156, v157
	v_cvt_pk_bf16_f32 v116, v158, v159
	v_cvt_pk_bf16_f32 v117, v160, v161
	v_mfma_f32_32x32x16_bf16 v[138:153], v[106:109], v[2:5], v[138:153]
	ds_read_b128 v[106:109], v84 offset:24576
	ds_read_b128 v[196:199], v89 offset:0
	v_exp_f32_e32 v162, v162
	v_exp_f32_e32 v163, v163
	v_mfma_f32_32x32x16_bf16 v[138:153], v[110:113], v[6:9], v[138:153]
	ds_read_b128 v[110:113], v85 offset:24576
	ds_read_b128 v[216:219], v89 offset:8192
	v_exp_f32_e32 v164, v164
	v_exp_f32_e32 v165, v165
	s_waitcnt lgkmcnt(8)
	v_mfma_f32_32x32x16_bf16 v[18:33], v[128:131], v[114:117], v[18:33]
	v_exp_f32_e32 v166, v166
	v_exp_f32_e32 v167, v167
	s_waitcnt lgkmcnt(6)
	v_mfma_f32_32x32x16_bf16 v[34:49], v[184:187], v[114:117], v[34:49]
	ds_read_b128 v[200:203], v89 offset:16384
	v_exp_f32_e32 v168, v168
	v_exp_f32_e32 v169, v169
	s_waitcnt lgkmcnt(6)
	v_mfma_f32_32x32x16_bf16 v[50:65], v[188:191], v[114:117], v[50:65]
	ds_read_b128 v[204:207], v89 offset:24576
	v_add_f32_e32 v122, v162, v122
	v_add_f32_e32 v122, v163, v122
	v_add_f32_e32 v122, v164, v122
	v_add_f32_e32 v122, v165, v122
	s_waitcnt lgkmcnt(6)
	v_mfma_f32_32x32x16_bf16 v[66:81], v[192:195], v[114:117], v[66:81]
	v_add_f32_e32 v122, v166, v122
	v_add_f32_e32 v122, v167, v122
	v_add_f32_e32 v122, v168, v122
	v_add_f32_e32 v122, v169, v122
	v_cvt_pk_bf16_f32 v118, v162, v163
	v_cvt_pk_bf16_f32 v119, v164, v165
	v_cvt_pk_bf16_f32 v120, v166, v167
	v_cvt_pk_bf16_f32 v121, v168, v169
	v_mfma_f32_32x32x16_bf16 v[154:169], v[98:101], v[10:13], 0
	ds_read_b128 v[128:131], v90 offset:0
	v_exp_f32_e32 v138, v138
	v_exp_f32_e32 v139, v139
	v_mfma_f32_32x32x16_bf16 v[154:169], v[102:105], v[14:17], v[154:169]
	ds_read_b128 v[184:187], v90 offset:8192
	v_exp_f32_e32 v140, v140
	v_exp_f32_e32 v141, v141
	s_waitcnt lgkmcnt(6)
	v_mfma_f32_32x32x16_bf16 v[18:33], v[196:199], v[118:121], v[18:33]
	v_exp_f32_e32 v142, v142
	v_exp_f32_e32 v143, v143
	s_waitcnt lgkmcnt(4)
	v_mfma_f32_32x32x16_bf16 v[34:49], v[216:219], v[118:121], v[34:49]
	ds_read_b128 v[188:191], v90 offset:16384
	v_exp_f32_e32 v144, v144
	v_exp_f32_e32 v145, v145
	s_waitcnt lgkmcnt(4)
	v_mfma_f32_32x32x16_bf16 v[50:65], v[200:203], v[118:121], v[50:65]
	ds_read_b128 v[192:195], v90 offset:24576
	v_add_f32_e32 v122, v138, v122
	v_add_f32_e32 v122, v139, v122
	v_add_f32_e32 v122, v140, v122
	v_add_f32_e32 v122, v141, v122
	s_waitcnt lgkmcnt(4)
	v_mfma_f32_32x32x16_bf16 v[66:81], v[204:207], v[118:121], v[66:81]
	v_add_f32_e32 v122, v142, v122
	v_add_f32_e32 v122, v143, v122
	v_add_f32_e32 v122, v144, v122
	v_add_f32_e32 v122, v145, v122
	v_cvt_pk_bf16_f32 v114, v138, v139
	v_cvt_pk_bf16_f32 v115, v140, v141
	v_cvt_pk_bf16_f32 v116, v142, v143
	v_cvt_pk_bf16_f32 v117, v144, v145
	v_mfma_f32_32x32x16_bf16 v[154:169], v[106:109], v[2:5], v[154:169]
	ds_read_b128 v[196:199], v91 offset:0
	v_exp_f32_e32 v146, v146
	v_exp_f32_e32 v147, v147
	v_mfma_f32_32x32x16_bf16 v[154:169], v[110:113], v[6:9], v[154:169]
	ds_read_b128 v[216:219], v91 offset:8192
	v_exp_f32_e32 v148, v148
	v_exp_f32_e32 v149, v149
	s_waitcnt lgkmcnt(5)
	v_mfma_f32_32x32x16_bf16 v[18:33], v[128:131], v[114:117], v[18:33]
	v_exp_f32_e32 v150, v150
	v_exp_f32_e32 v151, v151
	s_waitcnt lgkmcnt(4)
	v_mfma_f32_32x32x16_bf16 v[34:49], v[184:187], v[114:117], v[34:49]
	ds_read_b128 v[200:203], v91 offset:16384
	v_exp_f32_e32 v152, v152
	v_exp_f32_e32 v153, v153
	s_waitcnt lgkmcnt(4)
	v_mfma_f32_32x32x16_bf16 v[50:65], v[188:191], v[114:117], v[50:65]
	ds_read_b128 v[204:207], v91 offset:24576
	v_add_f32_e32 v122, v146, v122
	v_add_f32_e32 v122, v147, v122
	v_add_f32_e32 v122, v148, v122
	v_add_f32_e32 v122, v149, v122
	s_waitcnt lgkmcnt(4)
	v_mfma_f32_32x32x16_bf16 v[66:81], v[192:195], v[114:117], v[66:81]
	v_add_f32_e32 v122, v150, v122
	v_add_f32_e32 v122, v151, v122
	v_add_f32_e32 v122, v152, v122
	v_add_f32_e32 v122, v153, v122
	v_cvt_pk_bf16_f32 v118, v146, v147
	v_cvt_pk_bf16_f32 v119, v148, v149
	v_cvt_pk_bf16_f32 v120, v150, v151
	v_cvt_pk_bf16_f32 v121, v152, v153
	s_waitcnt lgkmcnt(3)
	s_nop 0
	v_mfma_f32_32x32x16_bf16 v[18:33], v[196:199], v[118:121], v[18:33]
	ds_read_b128 v[128:131], v92 offset:0
	v_exp_f32_e32 v154, v154
	v_exp_f32_e32 v155, v155
	v_exp_f32_e32 v156, v156
	s_waitcnt lgkmcnt(3)
	v_mfma_f32_32x32x16_bf16 v[34:49], v[216:219], v[118:121], v[34:49]
	ds_read_b128 v[184:187], v92 offset:8192
	v_exp_f32_e32 v157, v157
	v_exp_f32_e32 v158, v158
	v_exp_f32_e32 v159, v159
	s_waitcnt lgkmcnt(3)
	v_mfma_f32_32x32x16_bf16 v[50:65], v[200:203], v[118:121], v[50:65]
	ds_read_b128 v[188:191], v92 offset:16384
	v_exp_f32_e32 v160, v160
	v_exp_f32_e32 v161, v161
	v_add_f32_e32 v122, v154, v122
	v_add_f32_e32 v122, v155, v122
	s_waitcnt lgkmcnt(3)
	v_mfma_f32_32x32x16_bf16 v[66:81], v[204:207], v[118:121], v[66:81]
	ds_read_b128 v[192:195], v92 offset:24576
	v_add_f32_e32 v122, v156, v122
	v_add_f32_e32 v122, v157, v122
	v_add_f32_e32 v122, v158, v122
	v_add_f32_e32 v122, v159, v122
	v_add_f32_e32 v122, v160, v122
	v_add_f32_e32 v122, v161, v122
	v_cvt_pk_bf16_f32 v114, v154, v155
	v_cvt_pk_bf16_f32 v115, v156, v157
	v_cvt_pk_bf16_f32 v116, v158, v159
	v_cvt_pk_bf16_f32 v117, v160, v161
	s_waitcnt lgkmcnt(3)
	s_nop 0
	v_mfma_f32_32x32x16_bf16 v[18:33], v[128:131], v[114:117], v[18:33]
	ds_read_b128 v[196:199], v93 offset:0
	v_exp_f32_e32 v162, v162
	v_exp_f32_e32 v163, v163
	v_exp_f32_e32 v164, v164
	s_waitcnt lgkmcnt(3)
	v_mfma_f32_32x32x16_bf16 v[34:49], v[184:187], v[114:117], v[34:49]
	ds_read_b128 v[216:219], v93 offset:8192
	v_exp_f32_e32 v165, v165
	v_exp_f32_e32 v166, v166
	v_exp_f32_e32 v167, v167
	s_waitcnt lgkmcnt(3)
	v_mfma_f32_32x32x16_bf16 v[50:65], v[188:191], v[114:117], v[50:65]
	ds_read_b128 v[200:203], v93 offset:16384
	v_exp_f32_e32 v168, v168
	v_exp_f32_e32 v169, v169
	v_add_f32_e32 v122, v162, v122
	v_add_f32_e32 v122, v163, v122
	s_waitcnt lgkmcnt(3)
	v_mfma_f32_32x32x16_bf16 v[66:81], v[192:195], v[114:117], v[66:81]
	ds_read_b128 v[204:207], v93 offset:24576
	v_add_f32_e32 v122, v164, v122
	v_add_f32_e32 v122, v165, v122
	v_add_f32_e32 v122, v166, v122
	v_add_f32_e32 v122, v167, v122
	v_add_f32_e32 v122, v168, v122
	v_add_f32_e32 v122, v169, v122
	v_cvt_pk_bf16_f32 v118, v162, v163
	v_cvt_pk_bf16_f32 v119, v164, v165
	v_cvt_pk_bf16_f32 v120, v166, v167
	v_cvt_pk_bf16_f32 v121, v168, v169
	s_waitcnt lgkmcnt(3)
	s_nop 0
	v_mfma_f32_32x32x16_bf16 v[18:33], v[196:199], v[118:121], v[18:33]
	s_waitcnt lgkmcnt(2)
	v_mfma_f32_32x32x16_bf16 v[34:49], v[216:219], v[118:121], v[34:49]
	s_waitcnt lgkmcnt(1)
	v_mfma_f32_32x32x16_bf16 v[50:65], v[200:203], v[118:121], v[50:65]
	s_waitcnt lgkmcnt(0)
	v_mfma_f32_32x32x16_bf16 v[66:81], v[204:207], v[118:121], v[66:81]
	s_waitcnt vmcnt(0)
	s_waitcnt lgkmcnt(0)
	s_barrier
	v_readlane_b32 s64, v175, 0
	v_readlane_b32 s65, v175, 1
	v_readlane_b32 s66, v175, 2
	v_readlane_b32 s67, v175, 3
	v_readlane_b32 s68, v175, 4
	v_readlane_b32 s69, v175, 5
	v_readlane_b32 s70, v175, 6
	v_readlane_b32 s71, v175, 7
	v_readlane_b32 s72, v175, 8
	v_readlane_b32 s73, v175, 9
	v_readlane_b32 s74, v175, 10
	v_readlane_b32 s75, v175, 11
	v_readlane_b32 s76, v175, 12
	v_readlane_b32 s77, v175, 13
	v_readlane_b32 s78, v175, 14
	v_readlane_b32 s79, v175, 15
	s_nop 4
	s_mov_b32 s10, 0x3fb8aa3b
	s_mov_b32 s11, 0xc2ce8ed0
	s_mov_b32 s6, 0x42b17218
	v_cmp_eq_u32_e64 s[40:41], 0, v179
	s_lshl_b32 s30, s14, 1
	v_lshlrev_b32_e32 v196, 3, v178
	v_mov_b32_e32 v197, 0
	v_lshlrev_b32_e32 v198, 4, v179
	v_or3_b32 v198, v198, v177, v180
	v_ashrrev_i32_e32 v199, 31, v198
	v_lshlrev_b64 v[198:199], 11, v[198:199]
	s_mov_b64 s[100:101], 0x18a10000
	v_lshl_add_u64 v[198:199], s[42:43], 0, v[198:199]
	v_lshl_add_u64 v[198:199], v[198:199], 0, s[30:31]
	v_lshl_add_u64 v[198:199], v[198:199], 0, v[196:197]
	v_lshl_add_u64 v[198:199], v[198:199], 0, s[100:101]
	global_load_dwordx2 v[146:147], v[198:199], off
	global_load_dwordx2 v[148:149], v[198:199], off offset:32
	global_load_dwordx2 v[150:151], v[198:199], off offset:64
	global_load_dwordx2 v[152:153], v[198:199], off offset:96
	global_load_dwordx2 v[188:189], v[198:199], off offset:128
	global_load_dwordx2 v[190:191], v[198:199], off offset:160
	global_load_dwordx2 v[192:193], v[198:199], off offset:192
	global_load_dwordx2 v[194:195], v[198:199], off offset:224
	s_mov_b64 s[100:101], exec
	s_and_b64 exec, exec, s[4:5]
	s_cbranch_execz .Lpop_skip
	v_readlane_b32 s14, v255, 22
	v_readlane_b32 s15, v255, 23
	v_mov_b32_e32 v224, 1
	s_nop 4
	global_atomic_add v224, v0, v224, s[14:15] sc0
